# speedup vs baseline: 1.0156x; 1.0156x over previous
; DEVI float bflo(unsigned v) { return __uint_as_float(v << 16); }
; DEVI float bfhi(unsigned v) { return __uint_as_float(v & 0xffff0000u); }
; DEVI unsigned packbf(float a, float b) { fl2v v = {a, b}; bf2v r = __builtin_convertvector(v, bf2v); return __builtin_bit_cast(unsigned, r); }
; DEVI float sigm(float x) { return 1.f / (1.f + __expf(-x)); }
; DEVI void act_phase(int TID_, int BID_, PREF p, int g, int layer) {
;     ...
;     float w0[8], w1[8], w2[8], bb[8];
; #pragma unroll
;     for (int k = 0; k < 8; k += 4) {
;       float4 a0 = *(const float4*)(cw + j + k), a1 = *(const float4*)(cw + DFF + j + k), a2 = *(const float4*)(cw + 2 * DFF + j + k),
;              a3 = *(const float4*)(cb + j + k);
;       w0[k] = a0.x; w0[k + 1] = a0.y; w0[k + 2] = a0.z; w0[k + 3] = a0.w;
;       w1[k] = a1.x; w1[k + 1] = a1.y; w1[k + 2] = a1.z; w1[k + 3] = a1.w;
;       w2[k] = a2.x; w2[k + 1] = a2.y; w2[k + 2] = a2.z; w2[k + 3] = a2.w;
;       bb[k] = a3.x; bb[k + 1] = a3.y; bb[k + 2] = a3.z; bb[k + 3] = a3.w;
;     }
; #pragma unroll
;     for (int t = 0; t < 4; ++t) {
;       const unsigned gm[4] = {gr[t].x, gr[t].y, gr[t].z, gr[t].w}, g0[4] = {gr[t + 1].x, gr[t + 1].y, gr[t + 1].z, gr[t + 1].w},
;                      gp[4] = {gr[t + 2].x, gr[t + 2].y, gr[t + 2].z, gr[t + 2].w}, va[4] = {vr[t].x, vr[t].y, vr[t].z, vr[t].w};
;       unsigned o[4];
; #pragma unroll
;       for (int k = 0; k < 4; ++k) {
;         float a = bflo(gm[k]) * w0[2 * k] + bflo(g0[k]) * w1[2 * k] + bflo(gp[k]) * w2[2 * k] + bb[2 * k];
;         float b = bfhi(gm[k]) * w0[2 * k + 1] + bfhi(g0[k]) * w1[2 * k + 1] + bfhi(gp[k]) * w2[2 * k + 1] + bb[2 * k + 1];
;         o[k] = packbf(a * sigm(a) * bflo(va[k]), b * sigm(b) * bfhi(va[k]));
.LBB0_71:
	s_or_b64 exec, exec, s[20:21]
	v_lshlrev_b32_e32 v196, 3, v10
	v_lshlrev_b64 v[8:9], 2, v[196:197]
	s_waitcnt vmcnt(12)
	v_lshl_add_u64 v[12:13], s[10:11], 0, v[8:9]
	s_waitcnt vmcnt(10)
	v_lshl_add_u64 v[16:17], s[14:15], 0, v[8:9]
	v_lshl_add_u64 v[20:21], s[16:17], 0, v[8:9]
	s_waitcnt vmcnt(8)
	v_lshl_add_u64 v[36:37], s[12:13], 0, v[8:9]
	global_load_dwordx4 v[8:11], v[12:13], off offset:16
	global_load_dwordx4 v[24:27], v[12:13], off
	s_nop 0
	global_load_dwordx4 v[12:15], v[16:17], off offset:16
	global_load_dwordx4 v[28:31], v[16:17], off
	s_nop 0
	global_load_dwordx4 v[16:19], v[20:21], off offset:16
	global_load_dwordx4 v[32:35], v[20:21], off
	s_nop 0
	global_load_dwordx4 v[20:23], v[36:37], off offset:16
	s_nop 0
	global_load_dwordx4 v[36:39], v[36:37], off
	s_waitcnt vmcnt(15)
	v_lshlrev_b32_e32 v76, 16, v60
	v_and_b32_e32 v77, 0xffff0000, v60
	v_lshlrev_b32_e32 v80, 16, v56
	v_and_b32_e32 v81, 0xffff0000, v56
	s_waitcnt vmcnt(13)
	v_lshlrev_b32_e32 v74, 16, v68
	v_and_b32_e32 v75, 0xffff0000, v68
	v_lshlrev_b32_e32 v82, 16, v64
	v_and_b32_e32 v83, 0xffff0000, v64
	v_lshlrev_b32_e32 v196, 1, v196
	v_lshl_add_u64 v[78:79], s[8:9], 0, v[196:197]
	v_mul_u32_u24_e32 v196, 0x5800, v86
	v_lshl_add_u64 v[72:73], v[72:73], 0, s[50:51]
	s_waitcnt vmcnt(4)
	v_pk_mul_f32 v[84:85], v[28:29], v[76:77]
	s_nop 0
	v_pk_fma_f32 v[80:81], v[24:25], v[80:81], v[84:85]
	s_waitcnt vmcnt(2)
	v_pk_fma_f32 v[80:81], v[32:33], v[74:75], v[80:81]
	s_waitcnt vmcnt(0)
	v_pk_add_f32 v[80:81], v[80:81], v[36:37]
	s_nop 0
	v_mul_f32_e32 v56, 0xbfb8aa3b, v80
	v_exp_f32_e32 v84, v56
	v_mul_f32_e32 v56, 0xbfb8aa3b, v81
	v_exp_f32_e32 v85, v56
	s_nop 0
	v_pk_add_f32 v[84:85], v[84:85], 1.0 op_sel_hi:[1,0]
	s_nop 0
	v_div_scale_f32 v56, s[20:21], v85, v85, 1.0
	v_rcp_f32_e32 v60, v56
	s_nop 0
	v_fma_f32 v64, -v56, v60, 1.0
	v_fmac_f32_e32 v60, v64, v60
	v_div_scale_f32 v64, vcc, 1.0, v85, 1.0
	v_mul_f32_e32 v68, v64, v60
	v_fma_f32 v87, -v56, v68, v64
	v_fmac_f32_e32 v68, v87, v60
	v_fma_f32 v56, -v56, v68, v64
	v_div_fmas_f32 v56, v56, v60, v68
	v_div_fixup_f32 v85, v56, v85, 1.0
	v_div_scale_f32 v56, s[20:21], v84, v84, 1.0
	v_rcp_f32_e32 v60, v56
	s_nop 0
	v_fma_f32 v64, -v56, v60, 1.0
	v_fmac_f32_e32 v60, v64, v60
	v_div_scale_f32 v64, vcc, 1.0, v84, 1.0
	v_mul_f32_e32 v68, v64, v60
	v_fma_f32 v87, -v56, v68, v64
	v_fmac_f32_e32 v68, v87, v60
	v_fma_f32 v56, -v56, v68, v64
	v_div_fmas_f32 v56, v56, v60, v68
	v_div_fixup_f32 v84, v56, v84, 1.0
	v_pk_mul_f32 v[80:81], v[80:81], v[84:85]
	v_lshlrev_b32_e32 v60, 16, v65
	v_pk_mul_f32 v[80:81], v[80:81], v[82:83]
	v_lshlrev_b32_e32 v82, 16, v57
	v_cvt_pk_bf16_f32 v56, v80, v81
	v_lshlrev_b32_e32 v80, 16, v61
	v_and_b32_e32 v81, 0xffff0000, v61
	v_and_b32_e32 v83, 0xffff0000, v57
	v_and_b32_e32 v61, 0xffff0000, v65
	v_pk_mul_f32 v[64:65], v[30:31], v[80:81]
	v_lshlrev_b32_e32 v68, 16, v69
	v_and_b32_e32 v69, 0xffff0000, v69
	v_pk_fma_f32 v[64:65], v[26:27], v[82:83], v[64:65]
	s_nop 0
	v_pk_fma_f32 v[64:65], v[34:35], v[68:69], v[64:65]
	s_nop 0
	v_pk_add_f32 v[64:65], v[64:65], v[38:39]
	s_nop 0
	v_mul_f32_e32 v57, 0xbfb8aa3b, v64
	v_exp_f32_e32 v82, v57
	v_mul_f32_e32 v57, 0xbfb8aa3b, v65
	v_exp_f32_e32 v83, v57
	s_nop 0
	v_pk_add_f32 v[82:83], v[82:83], 1.0 op_sel_hi:[1,0]
	s_nop 0
	v_div_scale_f32 v57, s[20:21], v83, v83, 1.0
	v_rcp_f32_e32 v84, v57
	s_nop 0
	v_fma_f32 v85, -v57, v84, 1.0
	v_fmac_f32_e32 v84, v85, v84
	v_div_scale_f32 v85, vcc, 1.0, v83, 1.0
	v_mul_f32_e32 v87, v85, v84
	v_fma_f32 v88, -v57, v87, v85
	v_fmac_f32_e32 v87, v88, v84
	v_fma_f32 v57, -v57, v87, v85
	v_div_fmas_f32 v57, v57, v84, v87
	v_div_fixup_f32 v83, v57, v83, 1.0
	v_div_scale_f32 v57, s[20:21], v82, v82, 1.0
	v_rcp_f32_e32 v84, v57
	s_nop 0
	v_fma_f32 v85, -v57, v84, 1.0
	v_fmac_f32_e32 v84, v85, v84
	v_div_scale_f32 v85, vcc, 1.0, v82, 1.0
	v_mul_f32_e32 v87, v85, v84
	v_fma_f32 v88, -v57, v87, v85
	v_fmac_f32_e32 v87, v88, v84
	v_fma_f32 v57, -v57, v87, v85
	v_div_fmas_f32 v57, v57, v84, v87
	v_div_fixup_f32 v82, v57, v82, 1.0
	v_pk_mul_f32 v[64:65], v[64:65], v[82:83]
	v_lshlrev_b32_e32 v82, 16, v62
	v_pk_mul_f32 v[60:61], v[64:65], v[60:61]
	v_and_b32_e32 v83, 0xffff0000, v62
	v_cvt_pk_bf16_f32 v57, v60, v61
	v_lshlrev_b32_e32 v60, 16, v58
	v_and_b32_e32 v61, 0xffff0000, v58
	v_pk_mul_f32 v[88:89], v[12:13], v[82:83]
	v_lshlrev_b32_e32 v64, 16, v70
	v_and_b32_e32 v65, 0xffff0000, v70
	v_pk_fma_f32 v[60:61], v[8:9], v[60:61], v[88:89]
	v_lshlrev_b32_e32 v84, 16, v66
	v_pk_fma_f32 v[60:61], v[16:17], v[64:65], v[60:61]
	v_and_b32_e32 v85, 0xffff0000, v66
	v_pk_add_f32 v[60:61], v[60:61], v[20:21]
	s_nop 0
	v_mul_f32_e32 v58, 0xbfb8aa3b, v60
	v_exp_f32_e32 v88, v58
	v_mul_f32_e32 v58, 0xbfb8aa3b, v61
	v_exp_f32_e32 v89, v58
	s_nop 0
	v_pk_add_f32 v[88:89], v[88:89], 1.0 op_sel_hi:[1,0]
	s_nop 0
	v_div_scale_f32 v58, s[20:21], v89, v89, 1.0
	v_rcp_f32_e32 v62, v58
	s_nop 0
	v_fma_f32 v66, -v58, v62, 1.0
	v_fmac_f32_e32 v62, v66, v62
	v_div_scale_f32 v66, vcc, 1.0, v89, 1.0
	v_mul_f32_e32 v70, v66, v62
	v_fma_f32 v87, -v58, v70, v66
	v_fmac_f32_e32 v70, v87, v62
	v_fma_f32 v58, -v58, v70, v66
	v_div_fmas_f32 v58, v58, v62, v70
	v_div_fixup_f32 v89, v58, v89, 1.0
	v_div_scale_f32 v58, s[20:21], v88, v88, 1.0
	v_rcp_f32_e32 v62, v58
	s_nop 0
	v_fma_f32 v66, -v58, v62, 1.0
	v_fmac_f32_e32 v62, v66, v62
	v_div_scale_f32 v66, vcc, 1.0, v88, 1.0
	v_mul_f32_e32 v70, v66, v62
	v_fma_f32 v87, -v58, v70, v66
	v_fmac_f32_e32 v70, v87, v62
	v_fma_f32 v58, -v58, v70, v66
	v_div_fmas_f32 v58, v58, v62, v70
	v_div_fixup_f32 v88, v58, v88, 1.0
	v_pk_mul_f32 v[60:61], v[60:61], v[88:89]
	v_lshlrev_b32_e32 v62, 16, v71
; DEVI float bflo(unsigned v) { return __uint_as_float(v << 16); }
; DEVI float bfhi(unsigned v) { return __uint_as_float(v & 0xffff0000u); }
; DEVI unsigned packbf(float a, float b) { fl2v v = {a, b}; bf2v r = __builtin_convertvector(v, bf2v); return __builtin_bit_cast(unsigned, r); }
; DEVI float sigm(float x) { return 1.f / (1.f + __expf(-x)); }
; DEVI void act_phase(int TID_, int BID_, PREF p, int g, int layer) {
;     ...
;       for (int k = 0; k < 4; ++k) {
;         float a = bflo(gm[k]) * w0[2 * k] + bflo(g0[k]) * w1[2 * k] + bflo(gp[k]) * w2[2 * k] + bb[2 * k];
;         float b = bfhi(gm[k]) * w0[2 * k + 1] + bfhi(g0[k]) * w1[2 * k + 1] + bfhi(gp[k]) * w2[2 * k + 1] + bb[2 * k + 1];
;         o[k] = packbf(a * sigm(a) * bflo(va[k]), b * sigm(b) * bfhi(va[k]));
;       }
;       *(uint4*)(act + (size_t)(tok0 + t) * DFF + j) = make_uint4(o[0], o[1], o[2], o[3]);
	v_pk_mul_f32 v[60:61], v[60:61], v[84:85]
	v_lshlrev_b32_e32 v84, 16, v63
	v_and_b32_e32 v85, 0xffff0000, v63
	v_cvt_pk_bf16_f32 v58, v60, v61
	v_lshlrev_b32_e32 v60, 16, v59
	v_and_b32_e32 v61, 0xffff0000, v59
	v_and_b32_e32 v63, 0xffff0000, v71
	v_pk_mul_f32 v[70:71], v[14:15], v[84:85]
	v_lshlrev_b32_e32 v66, 16, v67
	v_pk_fma_f32 v[60:61], v[10:11], v[60:61], v[70:71]
	v_and_b32_e32 v67, 0xffff0000, v67
	v_pk_fma_f32 v[60:61], v[18:19], v[62:63], v[60:61]
	s_nop 0
	v_pk_add_f32 v[60:61], v[60:61], v[22:23]
	s_nop 0
	v_mul_f32_e32 v59, 0xbfb8aa3b, v60
	v_exp_f32_e32 v70, v59
	v_mul_f32_e32 v59, 0xbfb8aa3b, v61
	v_exp_f32_e32 v71, v59
	s_nop 0
	v_pk_add_f32 v[70:71], v[70:71], 1.0 op_sel_hi:[1,0]
	s_nop 0
	v_div_scale_f32 v59, s[20:21], v71, v71, 1.0
	v_rcp_f32_e32 v87, v59
	s_nop 0
	v_fma_f32 v88, -v59, v87, 1.0
	v_fmac_f32_e32 v87, v88, v87
	v_div_scale_f32 v88, vcc, 1.0, v71, 1.0
	v_mul_f32_e32 v89, v88, v87
	v_fma_f32 v90, -v59, v89, v88
	v_fmac_f32_e32 v89, v90, v87
	v_fma_f32 v59, -v59, v89, v88
	v_div_fmas_f32 v59, v59, v87, v89
	v_div_fixup_f32 v71, v59, v71, 1.0
	v_div_scale_f32 v59, s[20:21], v70, v70, 1.0
	v_rcp_f32_e32 v87, v59
	s_nop 0
	v_fma_f32 v88, -v59, v87, 1.0
	v_fmac_f32_e32 v87, v88, v87
	v_div_scale_f32 v88, vcc, 1.0, v70, 1.0
	v_mul_f32_e32 v89, v88, v87
	v_fma_f32 v90, -v59, v89, v88
	v_fmac_f32_e32 v89, v90, v87
	v_fma_f32 v59, -v59, v89, v88
	v_div_fmas_f32 v59, v59, v87, v89
	v_div_fixup_f32 v70, v59, v70, 1.0
	v_pk_mul_f32 v[60:61], v[60:61], v[70:71]
	s_nop 0
	v_pk_mul_f32 v[60:61], v[60:61], v[66:67]
	v_pk_mul_f32 v[66:67], v[28:29], v[74:75]
	v_cvt_pk_bf16_f32 v59, v60, v61
	v_lshl_add_u64 v[60:61], v[196:197], 1, v[78:79]
	global_store_dwordx4 v[60:61], v[56:59], off nt
	v_pk_fma_f32 v[66:67], v[24:25], v[76:77], v[66:67]
	s_nop 0
	v_lshlrev_b32_e32 v56, 16, v52
	v_and_b32_e32 v57, 0xffff0000, v52
	v_pk_fma_f32 v[66:67], v[32:33], v[56:57], v[66:67]
	v_lshlrev_b32_e32 v58, 16, v48
	v_pk_add_f32 v[66:67], v[66:67], v[36:37]
	v_and_b32_e32 v59, 0xffff0000, v48
	v_mul_f32_e32 v48, 0xbfb8aa3b, v66
	v_exp_f32_e32 v70, v48
	v_mul_f32_e32 v48, 0xbfb8aa3b, v67
	v_exp_f32_e32 v71, v48
	s_nop 0
	v_pk_add_f32 v[70:71], v[70:71], 1.0 op_sel_hi:[1,0]
	s_nop 0
	v_div_scale_f32 v48, s[20:21], v71, v71, 1.0
	v_rcp_f32_e32 v52, v48
	s_nop 0
	v_fma_f32 v76, -v48, v52, 1.0
	v_fmac_f32_e32 v52, v76, v52
	v_div_scale_f32 v76, vcc, 1.0, v71, 1.0
	v_mul_f32_e32 v77, v76, v52
	v_fma_f32 v78, -v48, v77, v76
	v_fmac_f32_e32 v77, v78, v52
	v_fma_f32 v48, -v48, v77, v76
	v_div_fmas_f32 v48, v48, v52, v77
	v_div_fixup_f32 v71, v48, v71, 1.0
	v_div_scale_f32 v48, s[20:21], v70, v70, 1.0
	v_rcp_f32_e32 v52, v48
	s_nop 0
	v_fma_f32 v76, -v48, v52, 1.0
	v_fmac_f32_e32 v52, v76, v52
	v_div_scale_f32 v76, vcc, 1.0, v70, 1.0
	v_mul_f32_e32 v77, v76, v52
	v_fma_f32 v78, -v48, v77, v76
	v_fmac_f32_e32 v77, v78, v52
	v_fma_f32 v48, -v48, v77, v76
	v_div_fmas_f32 v48, v48, v52, v77
	v_div_fixup_f32 v70, v48, v70, 1.0
	v_pk_mul_f32 v[66:67], v[66:67], v[70:71]
	v_lshlrev_b32_e32 v52, 16, v49
	v_pk_mul_f32 v[58:59], v[66:67], v[58:59]
	v_lshlrev_b32_e32 v66, 16, v53
	v_cvt_pk_bf16_f32 v48, v58, v59
	v_pk_mul_f32 v[58:59], v[30:31], v[68:69]
	v_and_b32_e32 v67, 0xffff0000, v53
	v_pk_fma_f32 v[58:59], v[26:27], v[80:81], v[58:59]
	v_and_b32_e32 v53, 0xffff0000, v49
	v_pk_fma_f32 v[58:59], v[34:35], v[66:67], v[58:59]
	s_nop 0
	v_pk_add_f32 v[58:59], v[58:59], v[38:39]
	s_nop 0
	v_mul_f32_e32 v49, 0xbfb8aa3b, v58
	v_exp_f32_e32 v70, v49
	v_mul_f32_e32 v49, 0xbfb8aa3b, v59
	v_exp_f32_e32 v71, v49
	s_nop 0
	v_pk_add_f32 v[70:71], v[70:71], 1.0 op_sel_hi:[1,0]
	s_nop 0
	v_div_scale_f32 v49, s[20:21], v71, v71, 1.0
	v_rcp_f32_e32 v76, v49
	s_nop 0
	v_fma_f32 v77, -v49, v76, 1.0
	v_fmac_f32_e32 v76, v77, v76
	v_div_scale_f32 v77, vcc, 1.0, v71, 1.0
	v_mul_f32_e32 v78, v77, v76
	v_fma_f32 v79, -v49, v78, v77
	v_fmac_f32_e32 v78, v79, v76
	v_fma_f32 v49, -v49, v78, v77
	v_div_fmas_f32 v49, v49, v76, v78
	v_div_fixup_f32 v71, v49, v71, 1.0
	v_div_scale_f32 v49, s[20:21], v70, v70, 1.0
	v_rcp_f32_e32 v76, v49
	s_nop 0
	v_fma_f32 v77, -v49, v76, 1.0
	v_fmac_f32_e32 v76, v77, v76
	v_div_scale_f32 v77, vcc, 1.0, v70, 1.0
	v_mul_f32_e32 v78, v77, v76
	v_fma_f32 v79, -v49, v78, v77
	v_fmac_f32_e32 v78, v79, v76
	v_fma_f32 v49, -v49, v78, v77
	v_div_fmas_f32 v49, v49, v76, v78
	v_div_fixup_f32 v70, v49, v70, 1.0
	v_pk_mul_f32 v[58:59], v[58:59], v[70:71]
	v_pk_mul_f32 v[70:71], v[12:13], v[64:65]
	v_pk_mul_f32 v[52:53], v[58:59], v[52:53]
	v_lshlrev_b32_e32 v58, 16, v54
	v_and_b32_e32 v59, 0xffff0000, v54
	v_pk_fma_f32 v[70:71], v[8:9], v[82:83], v[70:71]
	v_cvt_pk_bf16_f32 v49, v52, v53
	v_pk_fma_f32 v[70:71], v[16:17], v[58:59], v[70:71]
	v_lshlrev_b32_e32 v52, 16, v50
	v_pk_add_f32 v[70:71], v[70:71], v[20:21]
	v_and_b32_e32 v53, 0xffff0000, v50
	v_mul_f32_e32 v50, 0xbfb8aa3b, v70
	v_exp_f32_e32 v76, v50
	v_mul_f32_e32 v50, 0xbfb8aa3b, v71
	v_exp_f32_e32 v77, v50
	s_nop 0
	v_pk_add_f32 v[76:77], v[76:77], 1.0 op_sel_hi:[1,0]
	s_nop 0
	v_div_scale_f32 v50, s[20:21], v77, v77, 1.0
	v_rcp_f32_e32 v54, v50
	s_nop 0
	v_fma_f32 v78, -v50, v54, 1.0
	v_fmac_f32_e32 v54, v78, v54
	v_div_scale_f32 v78, vcc, 1.0, v77, 1.0
	v_mul_f32_e32 v79, v78, v54
	v_fma_f32 v80, -v50, v79, v78
	v_fmac_f32_e32 v79, v80, v54
	v_fma_f32 v50, -v50, v79, v78
	v_div_fmas_f32 v50, v50, v54, v79
	v_div_fixup_f32 v77, v50, v77, 1.0
	v_div_scale_f32 v50, s[20:21], v76, v76, 1.0
	v_rcp_f32_e32 v54, v50
	s_nop 0
	v_fma_f32 v78, -v50, v54, 1.0
	v_fmac_f32_e32 v54, v78, v54
	v_div_scale_f32 v78, vcc, 1.0, v76, 1.0
	v_mul_f32_e32 v79, v78, v54
	v_fma_f32 v80, -v50, v79, v78
	v_fmac_f32_e32 v79, v80, v54
; DEVI float bflo(unsigned v) { return __uint_as_float(v << 16); }
; DEVI float bfhi(unsigned v) { return __uint_as_float(v & 0xffff0000u); }
; DEVI unsigned packbf(float a, float b) { fl2v v = {a, b}; bf2v r = __builtin_convertvector(v, bf2v); return __builtin_bit_cast(unsigned, r); }
; DEVI float sigm(float x) { return 1.f / (1.f + __expf(-x)); }
; DEVI void act_phase(int TID_, int BID_, PREF p, int g, int layer) {
;     ...
;       for (int k = 0; k < 4; ++k) {
;         float a = bflo(gm[k]) * w0[2 * k] + bflo(g0[k]) * w1[2 * k] + bflo(gp[k]) * w2[2 * k] + bb[2 * k];
;         float b = bfhi(gm[k]) * w0[2 * k + 1] + bfhi(g0[k]) * w1[2 * k + 1] + bfhi(gp[k]) * w2[2 * k + 1] + bb[2 * k + 1];
;         o[k] = packbf(a * sigm(a) * bflo(va[k]), b * sigm(b) * bfhi(va[k]));
;       }
;       *(uint4*)(act + (size_t)(tok0 + t) * DFF + j) = make_uint4(o[0], o[1], o[2], o[3]);
	v_fma_f32 v50, -v50, v79, v78
	v_div_fmas_f32 v50, v50, v54, v79
	v_div_fixup_f32 v76, v50, v76, 1.0
	v_pk_mul_f32 v[70:71], v[70:71], v[76:77]
	v_lshlrev_b32_e32 v54, 16, v51
	v_pk_mul_f32 v[52:53], v[70:71], v[52:53]
	v_pk_mul_f32 v[70:71], v[14:15], v[62:63]
	v_cvt_pk_bf16_f32 v50, v52, v53
	v_lshlrev_b32_e32 v52, 16, v55
	v_and_b32_e32 v53, 0xffff0000, v55
	v_pk_fma_f32 v[70:71], v[10:11], v[84:85], v[70:71]
	v_and_b32_e32 v55, 0xffff0000, v51
	v_pk_fma_f32 v[70:71], v[18:19], v[52:53], v[70:71]
	s_nop 0
	v_pk_add_f32 v[70:71], v[70:71], v[22:23]
	s_nop 0
	v_mul_f32_e32 v51, 0xbfb8aa3b, v70
	v_exp_f32_e32 v76, v51
	v_mul_f32_e32 v51, 0xbfb8aa3b, v71
	v_exp_f32_e32 v77, v51
	s_nop 0
	v_pk_add_f32 v[76:77], v[76:77], 1.0 op_sel_hi:[1,0]
	s_nop 0
	v_div_scale_f32 v51, s[20:21], v77, v77, 1.0
	v_rcp_f32_e32 v78, v51
	s_nop 0
	v_fma_f32 v79, -v51, v78, 1.0
	v_fmac_f32_e32 v78, v79, v78
	v_div_scale_f32 v79, vcc, 1.0, v77, 1.0
	v_mul_f32_e32 v80, v79, v78
	v_fma_f32 v81, -v51, v80, v79
	v_fmac_f32_e32 v80, v81, v78
	v_fma_f32 v51, -v51, v80, v79
	v_div_fmas_f32 v51, v51, v78, v80
	v_div_fixup_f32 v77, v51, v77, 1.0
	v_div_scale_f32 v51, s[20:21], v76, v76, 1.0
	v_rcp_f32_e32 v78, v51
	s_movk_i32 s20, 0x2000
	v_fma_f32 v79, -v51, v78, 1.0
	v_fmac_f32_e32 v78, v79, v78
	v_div_scale_f32 v79, vcc, 1.0, v76, 1.0
	v_mul_f32_e32 v80, v79, v78
	v_fma_f32 v81, -v51, v80, v79
	v_fmac_f32_e32 v80, v81, v78
	v_fma_f32 v51, -v51, v80, v79
	v_div_fmas_f32 v51, v51, v78, v80
	v_div_fixup_f32 v76, v51, v76, 1.0
	v_pk_mul_f32 v[70:71], v[70:71], v[76:77]
	s_nop 0
	v_pk_mul_f32 v[54:55], v[70:71], v[54:55]
	s_nop 0
	v_cvt_pk_bf16_f32 v51, v54, v55
	v_add_co_u32_e32 v54, vcc, s20, v60
	s_nop 1
	v_addc_co_u32_e32 v55, vcc, 0, v61, vcc
	global_store_dwordx4 v[54:55], v[48:51], off offset:3072 nt
	v_lshlrev_b32_e32 v54, 16, v44
	v_and_b32_e32 v55, 0xffff0000, v44
	v_pk_mul_f32 v[50:51], v[28:29], v[56:57]
	v_lshlrev_b32_e32 v48, 16, v40
	v_pk_fma_f32 v[50:51], v[24:25], v[74:75], v[50:51]
	v_and_b32_e32 v49, 0xffff0000, v40
	v_pk_fma_f32 v[50:51], v[32:33], v[54:55], v[50:51]
	v_pk_mul_f32 v[28:29], v[28:29], v[54:55]
	v_pk_add_f32 v[50:51], v[50:51], v[36:37]
	v_pk_fma_f32 v[24:25], v[24:25], v[56:57], v[28:29]
	v_mul_f32_e32 v40, 0xbfb8aa3b, v50
	v_exp_f32_e32 v70, v40
	v_mul_f32_e32 v40, 0xbfb8aa3b, v51
	v_exp_f32_e32 v71, v40
	v_lshlrev_b32_e32 v28, 16, v0
	v_and_b32_e32 v29, 0xffff0000, v0
	v_pk_fma_f32 v[24:25], v[32:33], v[28:29], v[24:25]
	v_pk_add_f32 v[70:71], v[70:71], 1.0 op_sel_hi:[1,0]
	v_pk_add_f32 v[24:25], v[24:25], v[36:37]
	v_div_scale_f32 v40, s[20:21], v71, v71, 1.0
	v_rcp_f32_e32 v44, v40
	v_mul_f32_e32 v0, 0xbfb8aa3b, v24
	v_exp_f32_e32 v28, v0
	v_mul_f32_e32 v0, 0xbfb8aa3b, v25
	v_fma_f32 v74, -v40, v44, 1.0
	v_fmac_f32_e32 v44, v74, v44
	v_div_scale_f32 v74, vcc, 1.0, v71, 1.0
	v_mul_f32_e32 v75, v74, v44
	v_fma_f32 v76, -v40, v75, v74
	v_fmac_f32_e32 v75, v76, v44
	v_fma_f32 v40, -v40, v75, v74
	v_div_fmas_f32 v40, v40, v44, v75
	v_div_fixup_f32 v71, v40, v71, 1.0
	v_div_scale_f32 v40, s[20:21], v70, v70, 1.0
	v_rcp_f32_e32 v44, v40
	v_exp_f32_e32 v29, v0
	v_fma_f32 v74, -v40, v44, 1.0
	v_fmac_f32_e32 v44, v74, v44
	v_div_scale_f32 v74, vcc, 1.0, v70, 1.0
	v_mul_f32_e32 v75, v74, v44
	v_fma_f32 v76, -v40, v75, v74
	v_fmac_f32_e32 v75, v76, v44
	v_fma_f32 v40, -v40, v75, v74
	v_div_fmas_f32 v40, v40, v44, v75
	v_div_fixup_f32 v70, v40, v70, 1.0
	v_pk_mul_f32 v[50:51], v[50:51], v[70:71]
	v_lshlrev_b32_e32 v44, 16, v41
	v_pk_mul_f32 v[48:49], v[50:51], v[48:49]
	v_lshlrev_b32_e32 v50, 16, v45
	v_cvt_pk_bf16_f32 v40, v48, v49
	v_pk_mul_f32 v[48:49], v[30:31], v[66:67]
	v_and_b32_e32 v51, 0xffff0000, v45
	v_pk_fma_f32 v[48:49], v[26:27], v[68:69], v[48:49]
	v_and_b32_e32 v45, 0xffff0000, v41
	v_pk_fma_f32 v[48:49], v[34:35], v[50:51], v[48:49]
	v_pk_add_f32 v[28:29], v[28:29], 1.0 op_sel_hi:[1,0]
	v_pk_add_f32 v[48:49], v[48:49], v[38:39]
	s_nop 0
	v_mul_f32_e32 v41, 0xbfb8aa3b, v48
	v_exp_f32_e32 v68, v41
	v_mul_f32_e32 v41, 0xbfb8aa3b, v49
	v_exp_f32_e32 v69, v41
	s_nop 0
	v_pk_add_f32 v[68:69], v[68:69], 1.0 op_sel_hi:[1,0]
	s_nop 0
	v_div_scale_f32 v41, s[20:21], v69, v69, 1.0
	v_rcp_f32_e32 v70, v41
	s_nop 0
	v_fma_f32 v71, -v41, v70, 1.0
	v_fmac_f32_e32 v70, v71, v70
	v_div_scale_f32 v71, vcc, 1.0, v69, 1.0
	v_mul_f32_e32 v74, v71, v70
	v_fma_f32 v75, -v41, v74, v71
	v_fmac_f32_e32 v74, v75, v70
	v_fma_f32 v41, -v41, v74, v71
	v_div_fmas_f32 v41, v41, v70, v74
	v_div_fixup_f32 v69, v41, v69, 1.0
	v_div_scale_f32 v41, s[20:21], v68, v68, 1.0
	v_rcp_f32_e32 v70, v41
	s_nop 0
	v_fma_f32 v71, -v41, v70, 1.0
	v_fmac_f32_e32 v70, v71, v70
	v_div_scale_f32 v71, vcc, 1.0, v68, 1.0
	v_mul_f32_e32 v74, v71, v70
	v_fma_f32 v75, -v41, v74, v71
	v_fmac_f32_e32 v74, v75, v70
	v_fma_f32 v41, -v41, v74, v71
	v_div_fmas_f32 v41, v41, v70, v74
	v_div_fixup_f32 v68, v41, v68, 1.0
	v_pk_mul_f32 v[48:49], v[48:49], v[68:69]
	v_pk_mul_f32 v[68:69], v[12:13], v[58:59]
	v_pk_mul_f32 v[44:45], v[48:49], v[44:45]
	v_lshlrev_b32_e32 v48, 16, v46
	v_and_b32_e32 v49, 0xffff0000, v46
	v_pk_fma_f32 v[64:65], v[8:9], v[64:65], v[68:69]
	v_cvt_pk_bf16_f32 v41, v44, v45
	v_pk_fma_f32 v[64:65], v[16:17], v[48:49], v[64:65]
	v_lshlrev_b32_e32 v44, 16, v42
	v_pk_add_f32 v[64:65], v[64:65], v[20:21]
	v_and_b32_e32 v45, 0xffff0000, v42
	v_mul_f32_e32 v42, 0xbfb8aa3b, v64
	v_exp_f32_e32 v68, v42
	v_mul_f32_e32 v42, 0xbfb8aa3b, v65
	v_exp_f32_e32 v69, v42
	v_pk_mul_f32 v[12:13], v[12:13], v[48:49]
	v_pk_add_f32 v[68:69], v[68:69], 1.0 op_sel_hi:[1,0]
	s_nop 0
	v_div_scale_f32 v42, s[20:21], v69, v69, 1.0
	v_rcp_f32_e32 v46, v42
	v_pk_fma_f32 v[8:9], v[8:9], v[58:59], v[12:13]
; DEVI float bflo(unsigned v) { return __uint_as_float(v << 16); }
; DEVI float bfhi(unsigned v) { return __uint_as_float(v & 0xffff0000u); }
; DEVI unsigned packbf(float a, float b) { fl2v v = {a, b}; bf2v r = __builtin_convertvector(v, bf2v); return __builtin_bit_cast(unsigned, r); }
; DEVI float sigm(float x) { return 1.f / (1.f + __expf(-x)); }
; DEVI void act_phase(int TID_, int BID_, PREF p, int g, int layer) {
;     ...
;       for (int k = 0; k < 4; ++k) {
;         float a = bflo(gm[k]) * w0[2 * k] + bflo(g0[k]) * w1[2 * k] + bflo(gp[k]) * w2[2 * k] + bb[2 * k];
;         float b = bfhi(gm[k]) * w0[2 * k + 1] + bfhi(g0[k]) * w1[2 * k + 1] + bfhi(gp[k]) * w2[2 * k + 1] + bb[2 * k + 1];
;         o[k] = packbf(a * sigm(a) * bflo(va[k]), b * sigm(b) * bfhi(va[k]));
;       }
;       *(uint4*)(act + (size_t)(tok0 + t) * DFF + j) = make_uint4(o[0], o[1], o[2], o[3]);
	v_lshlrev_b32_e32 v12, 16, v2
	v_and_b32_e32 v13, 0xffff0000, v2
	v_fma_f32 v70, -v42, v46, 1.0
	v_fmac_f32_e32 v46, v70, v46
	v_div_scale_f32 v70, vcc, 1.0, v69, 1.0
	v_mul_f32_e32 v71, v70, v46
	v_fma_f32 v74, -v42, v71, v70
	v_fmac_f32_e32 v71, v74, v46
	v_fma_f32 v42, -v42, v71, v70
	v_div_fmas_f32 v42, v42, v46, v71
	v_div_fixup_f32 v69, v42, v69, 1.0
	v_div_scale_f32 v42, s[20:21], v68, v68, 1.0
	v_rcp_f32_e32 v46, v42
	v_pk_fma_f32 v[8:9], v[16:17], v[12:13], v[8:9]
	v_fma_f32 v70, -v42, v46, 1.0
	v_fmac_f32_e32 v46, v70, v46
	v_div_scale_f32 v70, vcc, 1.0, v68, 1.0
	v_mul_f32_e32 v71, v70, v46
	v_fma_f32 v74, -v42, v71, v70
	v_fmac_f32_e32 v71, v74, v46
	v_fma_f32 v42, -v42, v71, v70
	v_div_fmas_f32 v42, v42, v46, v71
	v_div_fixup_f32 v68, v42, v68, 1.0
	v_pk_mul_f32 v[64:65], v[64:65], v[68:69]
	v_lshlrev_b32_e32 v46, 16, v43
	v_pk_mul_f32 v[44:45], v[64:65], v[44:45]
	v_pk_mul_f32 v[64:65], v[14:15], v[52:53]
	v_cvt_pk_bf16_f32 v42, v44, v45
	v_lshlrev_b32_e32 v44, 16, v47
	v_and_b32_e32 v45, 0xffff0000, v47
	v_pk_fma_f32 v[62:63], v[10:11], v[62:63], v[64:65]
	v_and_b32_e32 v47, 0xffff0000, v43
	v_pk_fma_f32 v[62:63], v[18:19], v[44:45], v[62:63]
	v_pk_add_f32 v[8:9], v[8:9], v[20:21]
	v_pk_add_f32 v[62:63], v[62:63], v[22:23]
	v_mul_f32_e32 v2, 0xbfb8aa3b, v8
	v_mul_f32_e32 v43, 0xbfb8aa3b, v62
	v_exp_f32_e32 v64, v43
	v_mul_f32_e32 v43, 0xbfb8aa3b, v63
	v_exp_f32_e32 v65, v43
	v_exp_f32_e32 v12, v2
	v_mul_f32_e32 v2, 0xbfb8aa3b, v9
	v_exp_f32_e32 v13, v2
	v_pk_add_f32 v[64:65], v[64:65], 1.0 op_sel_hi:[1,0]
	v_pk_add_f32 v[12:13], v[12:13], 1.0 op_sel_hi:[1,0]
	v_div_scale_f32 v43, s[20:21], v65, v65, 1.0
	v_rcp_f32_e32 v68, v43
	s_nop 0
	v_fma_f32 v69, -v43, v68, 1.0
	v_fmac_f32_e32 v68, v69, v68
	v_div_scale_f32 v69, vcc, 1.0, v65, 1.0
	v_mul_f32_e32 v70, v69, v68
	v_fma_f32 v71, -v43, v70, v69
	v_fmac_f32_e32 v70, v71, v68
	v_fma_f32 v43, -v43, v70, v69
	v_div_fmas_f32 v43, v43, v68, v70
	v_div_fixup_f32 v65, v43, v65, 1.0
	v_div_scale_f32 v43, s[20:21], v64, v64, 1.0
	v_rcp_f32_e32 v68, v43
	s_movk_i32 s20, 0x5000
	v_fma_f32 v69, -v43, v68, 1.0
	v_fmac_f32_e32 v68, v69, v68
	v_div_scale_f32 v69, vcc, 1.0, v64, 1.0
	v_mul_f32_e32 v70, v69, v68
	v_fma_f32 v71, -v43, v70, v69
	v_fmac_f32_e32 v70, v71, v68
	v_fma_f32 v43, -v43, v70, v69
	v_div_fmas_f32 v43, v43, v68, v70
	v_div_fixup_f32 v64, v43, v64, 1.0
	v_pk_mul_f32 v[62:63], v[62:63], v[64:65]
	s_nop 0
	v_pk_mul_f32 v[46:47], v[62:63], v[46:47]
	s_nop 0
	v_cvt_pk_bf16_f32 v43, v46, v47
	v_add_co_u32_e32 v46, vcc, s20, v60
	v_div_scale_f32 v0, s[20:21], v29, v29, 1.0
	s_nop 0
	v_addc_co_u32_e32 v47, vcc, 0, v61, vcc
	global_store_dwordx4 v[46:47], v[40:43], off offset:2048 nt
	v_div_scale_f32 v2, s[20:21], v13, v13, 1.0
	s_nop 0
	v_lshlrev_b32_e32 v40, 16, v4
	v_and_b32_e32 v41, 0xffff0000, v4
	v_rcp_f32_e32 v4, v0
	s_nop 0
	v_fma_f32 v32, -v0, v4, 1.0
	v_fmac_f32_e32 v4, v32, v4
	v_div_scale_f32 v32, vcc, 1.0, v29, 1.0
	v_mul_f32_e32 v33, v32, v4
	v_fma_f32 v36, -v0, v33, v32
	v_fmac_f32_e32 v33, v36, v4
	v_fma_f32 v0, -v0, v33, v32
	v_div_fmas_f32 v0, v0, v4, v33
	v_div_fixup_f32 v29, v0, v29, 1.0
	v_div_scale_f32 v0, s[20:21], v28, v28, 1.0
	v_rcp_f32_e32 v4, v0
	s_nop 0
	v_fma_f32 v32, -v0, v4, 1.0
	v_fmac_f32_e32 v4, v32, v4
	v_div_scale_f32 v32, vcc, 1.0, v28, 1.0
	v_mul_f32_e32 v33, v32, v4
	v_fma_f32 v36, -v0, v33, v32
	v_fmac_f32_e32 v33, v36, v4
	v_fma_f32 v0, -v0, v33, v32
	v_div_fmas_f32 v0, v0, v4, v33
	v_div_fixup_f32 v28, v0, v28, 1.0
	v_pk_mul_f32 v[24:25], v[24:25], v[28:29]
	v_lshlrev_b32_e32 v4, 16, v5
	v_pk_mul_f32 v[24:25], v[24:25], v[40:41]
	v_and_b32_e32 v5, 0xffff0000, v5
	v_cvt_pk_bf16_f32 v0, v24, v25
	v_pk_mul_f32 v[24:25], v[30:31], v[50:51]
	s_nop 0
	v_pk_fma_f32 v[24:25], v[26:27], v[66:67], v[24:25]
; DEVI float bflo(unsigned v) { return __uint_as_float(v << 16); }
; DEVI float bfhi(unsigned v) { return __uint_as_float(v & 0xffff0000u); }
; DEVI unsigned packbf(float a, float b) { fl2v v = {a, b}; bf2v r = __builtin_convertvector(v, bf2v); return __builtin_bit_cast(unsigned, r); }
; DEVI float sigm(float x) { return 1.f / (1.f + __expf(-x)); }
; DEVI void act_phase(int TID_, int BID_, PREF p, int g, int layer) {
;     ...
;   for (size_t idx = (size_t)BID_ * 512 + TID_; idx < total; idx += (size_t)gridDim.x * 512) {
;     ...
;       for (int k = 0; k < 4; ++k) {
;         float a = bflo(gm[k]) * w0[2 * k] + bflo(g0[k]) * w1[2 * k] + bflo(gp[k]) * w2[2 * k] + bb[2 * k];
;         float b = bfhi(gm[k]) * w0[2 * k + 1] + bfhi(g0[k]) * w1[2 * k + 1] + bfhi(gp[k]) * w2[2 * k + 1] + bb[2 * k + 1];
;         o[k] = packbf(a * sigm(a) * bflo(va[k]), b * sigm(b) * bfhi(va[k]));
;       }
;       *(uint4*)(act + (size_t)(tok0 + t) * DFF + j) = make_uint4(o[0], o[1], o[2], o[3]);
;     }
	v_lshlrev_b32_e32 v26, 16, v1
	v_and_b32_e32 v27, 0xffff0000, v1
	v_pk_fma_f32 v[24:25], v[34:35], v[26:27], v[24:25]
	s_nop 0
	v_pk_add_f32 v[24:25], v[24:25], v[38:39]
	s_nop 0
	v_mul_f32_e32 v1, 0xbfb8aa3b, v24
	v_exp_f32_e32 v26, v1
	v_mul_f32_e32 v1, 0xbfb8aa3b, v25
	v_exp_f32_e32 v27, v1
	s_nop 0
	v_pk_add_f32 v[26:27], v[26:27], 1.0 op_sel_hi:[1,0]
	s_nop 0
	v_div_scale_f32 v1, s[20:21], v27, v27, 1.0
	v_rcp_f32_e32 v28, v1
	s_nop 0
	v_fma_f32 v29, -v1, v28, 1.0
	v_fmac_f32_e32 v28, v29, v28
	v_div_scale_f32 v29, vcc, 1.0, v27, 1.0
	v_mul_f32_e32 v30, v29, v28
	v_fma_f32 v31, -v1, v30, v29
	v_fmac_f32_e32 v30, v31, v28
	v_fma_f32 v1, -v1, v30, v29
	v_div_fmas_f32 v1, v1, v28, v30
	v_div_fixup_f32 v27, v1, v27, 1.0
	v_div_scale_f32 v1, s[20:21], v26, v26, 1.0
	v_rcp_f32_e32 v28, v1
	s_nop 0
	v_fma_f32 v29, -v1, v28, 1.0
	v_fmac_f32_e32 v28, v29, v28
	v_div_scale_f32 v29, vcc, 1.0, v26, 1.0
	v_mul_f32_e32 v30, v29, v28
	v_fma_f32 v31, -v1, v30, v29
	v_fmac_f32_e32 v30, v31, v28
	v_fma_f32 v1, -v1, v30, v29
	v_div_fmas_f32 v1, v1, v28, v30
	v_div_fixup_f32 v26, v1, v26, 1.0
	v_pk_mul_f32 v[24:25], v[24:25], v[26:27]
	s_nop 0
	v_pk_mul_f32 v[4:5], v[24:25], v[4:5]
	s_nop 0
	v_cvt_pk_bf16_f32 v1, v4, v5
	v_lshlrev_b32_e32 v4, 16, v6
	v_and_b32_e32 v5, 0xffff0000, v6
	v_rcp_f32_e32 v6, v2
	s_nop 0
	v_fma_f32 v16, -v2, v6, 1.0
	v_fmac_f32_e32 v6, v16, v6
	v_div_scale_f32 v16, vcc, 1.0, v13, 1.0
	v_mul_f32_e32 v17, v16, v6
	v_fma_f32 v20, -v2, v17, v16
	v_fmac_f32_e32 v17, v20, v6
	v_fma_f32 v2, -v2, v17, v16
	v_div_fmas_f32 v2, v2, v6, v17
	v_div_fixup_f32 v13, v2, v13, 1.0
	v_div_scale_f32 v2, s[20:21], v12, v12, 1.0
	v_rcp_f32_e32 v6, v2
	s_nop 0
	v_fma_f32 v16, -v2, v6, 1.0
	v_fmac_f32_e32 v6, v16, v6
	v_div_scale_f32 v16, vcc, 1.0, v12, 1.0
	v_mul_f32_e32 v17, v16, v6
	v_fma_f32 v20, -v2, v17, v16
	v_fmac_f32_e32 v17, v20, v6
	v_fma_f32 v2, -v2, v17, v16
	v_div_fmas_f32 v2, v2, v6, v17
	v_div_fixup_f32 v12, v2, v12, 1.0
	v_pk_mul_f32 v[8:9], v[8:9], v[12:13]
	s_nop 0
	v_pk_mul_f32 v[4:5], v[8:9], v[4:5]
	v_lshlrev_b32_e32 v8, 16, v3
	v_cvt_pk_bf16_f32 v2, v4, v5
	v_lshlrev_b32_e32 v4, 16, v7
	v_and_b32_e32 v5, 0xffff0000, v7
	v_pk_mul_f32 v[6:7], v[14:15], v[44:45]
	v_and_b32_e32 v9, 0xffff0000, v3
	v_pk_fma_f32 v[6:7], v[10:11], v[52:53], v[6:7]
	s_nop 0
	v_pk_fma_f32 v[6:7], v[18:19], v[8:9], v[6:7]
	s_nop 0
	v_pk_add_f32 v[6:7], v[6:7], v[22:23]
	s_nop 0
	v_mul_f32_e32 v3, 0xbfb8aa3b, v6
	v_exp_f32_e32 v8, v3
	v_mul_f32_e32 v3, 0xbfb8aa3b, v7
	v_exp_f32_e32 v9, v3
	s_nop 0
	v_pk_add_f32 v[8:9], v[8:9], 1.0 op_sel_hi:[1,0]
	s_nop 0
	v_div_scale_f32 v3, s[20:21], v9, v9, 1.0
	v_rcp_f32_e32 v10, v3
	s_nop 0
	v_fma_f32 v11, -v3, v10, 1.0
	v_fmac_f32_e32 v10, v11, v10
	v_div_scale_f32 v11, vcc, 1.0, v9, 1.0
	v_mul_f32_e32 v12, v11, v10
	v_fma_f32 v13, -v3, v12, v11
	v_fmac_f32_e32 v12, v13, v10
	v_fma_f32 v3, -v3, v12, v11
	v_div_fmas_f32 v3, v3, v10, v12
	v_div_fixup_f32 v9, v3, v9, 1.0
	v_div_scale_f32 v3, s[20:21], v8, v8, 1.0
	v_rcp_f32_e32 v10, v3
	s_mov_b64 s[20:21], 0x2bffff
	v_fma_f32 v11, -v3, v10, 1.0
	v_fmac_f32_e32 v10, v11, v10
	v_div_scale_f32 v11, vcc, 1.0, v8, 1.0
	v_mul_f32_e32 v12, v11, v10
	v_fma_f32 v13, -v3, v12, v11
	v_fmac_f32_e32 v12, v13, v10
	v_fma_f32 v3, -v3, v12, v11
	v_div_fmas_f32 v3, v3, v10, v12
	v_div_fixup_f32 v8, v3, v8, 1.0
	v_pk_mul_f32 v[6:7], v[6:7], v[8:9]
	s_nop 0
	v_pk_mul_f32 v[4:5], v[6:7], v[4:5]
	s_nop 0
	v_cvt_pk_bf16_f32 v3, v4, v5
	v_add_co_u32_e32 v4, vcc, 0x8000, v60
	s_nop 1
	v_addc_co_u32_e32 v5, vcc, 0, v61, vcc
	v_cmp_lt_u64_e32 vcc, s[20:21], v[72:73]
	s_or_b64 s[18:19], vcc, s[18:19]
	global_store_dwordx4 v[4:5], v[0:3], off offset:1024 nt
	s_andn2_b64 exec, exec, s[18:19]
	s_cbranch_execz .LBB0_76

; DEVI void act_phase(int TID_, int BID_, PREF p, int g, int layer) {
;     ...
;     const u16* up = u + (size_t)tok0 * (2 * DFF) + j;
;     uint4 gr[6], vr[4];
;     gr[0] = ts0 > 0 ? *(const uint4*)(up - 2 * DFF) : make_uint4(0, 0, 0, 0);
; #pragma unroll
;     for (int t = 0; t < 4; ++t) { gr[t + 1] = *(const uint4*)(up + (size_t)t * 2 * DFF); vr[t] = *(const uint4*)(up + (size_t)t * 2 * DFF + DFF); }
;     gr[5] = ts0 + 4 < Ts ? *(const uint4*)(up + (size_t)4 * 2 * DFF) : make_uint4(0, 0, 0, 0);
.LBB0_74:
	s_or_b64 exec, exec, s[20:21]
	v_add_co_u32_e32 v2, vcc, 0x2000, v8
	s_nop 1
	v_addc_co_u32_e32 v3, vcc, 0, v9, vcc
	global_load_dwordx4 v[60:63], v[8:9], off
	global_load_dwordx4 v[64:67], v[2:3], off offset:3072 nt
	v_add_co_u32_e32 v2, vcc, 0x5000, v8
	s_nop 1
	v_addc_co_u32_e32 v3, vcc, 0, v9, vcc
	v_add_co_u32_e32 v4, vcc, 0x8000, v8
	s_nop 1
	v_addc_co_u32_e32 v5, vcc, 0, v9, vcc
	global_load_dwordx4 v[68:71], v[2:3], off offset:2048 nt
	global_load_dwordx4 v[48:51], v[4:5], off offset:1024 nt
	v_add_co_u32_e32 v2, vcc, 0xb000, v8
	s_nop 1
	v_addc_co_u32_e32 v3, vcc, 0, v9, vcc
	v_add_co_u32_e32 v4, vcc, 0xd000, v8
	s_nop 1
	v_addc_co_u32_e32 v5, vcc, 0, v9, vcc
	global_load_dwordx4 v[52:55], v[2:3], off nt
	global_load_dwordx4 v[40:43], v[4:5], off offset:3072 nt
	v_add_co_u32_e32 v2, vcc, 0x10000, v8
	s_nop 1
	v_addc_co_u32_e32 v3, vcc, 0, v9, vcc
	v_add_co_u32_e32 v4, vcc, 0x13000, v8
	s_nop 1
	v_addc_co_u32_e32 v5, vcc, 0, v9, vcc
	global_load_dwordx4 v[44:47], v[2:3], off offset:2048
	s_nop 0
	global_load_dwordx4 v[4:7], v[4:5], off offset:1024 nt
	v_cmp_gt_u32_e32 vcc, s22, v1
	v_mov_b32_e32 v1, 0
	v_mov_b32_e32 v2, 0
	v_mov_b32_e32 v3, 0
	s_and_saveexec_b64 s[20:21], vcc
	s_cbranch_execz .LBB0_71
	v_add_co_u32_e32 v0, vcc, 0x16000, v8
	s_nop 1
	v_addc_co_u32_e32 v1, vcc, 0, v9, vcc
	global_load_dwordx4 v[0:3], v[0:1], off
	s_branch .LBB0_71
